# phase A: tril-weight conversion loop moved to blocks 48-175 so no block carries both the dt-column gather and this loop after its rmsnorm rows
# speedup vs baseline: 1.0048x; 1.0048x over previous
; __device__ __forceinline__ u16 f2bf(float f) { return (u16)(cvt_pk(f, 0.f) & 0xffffu); }
; __device__ __forceinline__ void phaseA(const Params& p, const int wv, const int rep) {
;     ...
;   for (int i = blockIdx.x * NTHREADS + tid; i < 16384; i += gridDim.x * NTHREADS) {
;     int k = i & 1023, hh = i >> 10;
;     ((u16*)(ws + OFF_WDT))[i] = f2bf(p.in[8][(size_t)k * 7184 + 3584 + hh]);
;   }
;   u16* WSB = (u16*)(ws + OFF_WSB);
;   for (int i = blockIdx.x * NTHREADS + tid; i < 65536; i += gridDim.x * NTHREADS) {
;     int s = i & 127, tt = (i >> 7) & 127;
;     WSB[i] = f2bf(s <= tt ? p.in[11][i] : 0.f);
;   }
.LBB0_113:
	s_or_b64 exec, exec, s[0:1]
	v_readlane_b32 s2, v251, 1
	s_nop 3
	s_cmp_lg_u32 s2, 0x100
	s_cbranch_scc1 .Lwsb_keep
	v_subrev_u32_e32 v6, 0xa000, v6
	v_and_b32_e32 v6, 0x1ffff, v6
.Lwsb_keep:
	s_add_u32 s2, s50, 0x2600000
	s_mov_b32 s0, 0x10000
	s_addc_u32 s3, s51, 0
	v_cmp_gt_i32_e32 vcc, s0, v6
	s_and_saveexec_b64 s[0:1], vcc
	s_cbranch_execz .LBB0_118
	v_readlane_b32 s8, v251, 1
	s_lshl_b32 s12, s8, 9
	s_mov_b64 s[8:9], 0
	s_mov_b32 s13, 0xffff
	v_mov_b32_e32 v2, v6
	s_branch .LBB0_116
